# S5 final-pass prefix: batch the serialized S5E loads (8 in flight, counted vmcnt) in the chunk-prefix loops
# speedup vs baseline: 1.0070x; 1.0070x over previous
.LBB0_93:
	s_add_i32 s14, s10, 2
	s_add_u32 s15, s8, 0x80
	s_addc_u32 s11, s9, 0
	s_add_i32 vcc_lo, 0, 0x10000
	s_cmp_eq_u32 s73, s10
	s_cselect_b32 s11, s67, s11
	s_cselect_b32 s10, s66, s15
	s_cselect_b32 s45, s69, s13
	s_cselect_b32 s44, s68, s12
	s_add_i32 s15, 0, 0x14000
	v_add_u32_e32 v140, vcc_lo, v229
	v_add_u32_e32 v156, s15, v229
	ds_read_b128 v[128:131], v140
	ds_read_b128 v[132:135], v140 offset:1024
	ds_read_b128 v[136:139], v140 offset:2048
	ds_read_b128 v[140:143], v140 offset:3072
	ds_read_b128 v[144:147], v156
	ds_read_b128 v[148:151], v156 offset:1024
	ds_read_b128 v[152:155], v156 offset:2048
	ds_read_b128 v[156:159], v156 offset:3072
	v_lshl_add_u64 v[202:203], s[8:9], 0, v[188:189]
	s_add_i32 m0, s21, 0xc000
	ds_read_b128 v[160:163], v231
	ds_read_b128 v[164:167], v231 offset:1024
	ds_read_b128 v[168:171], v231 offset:2048
	ds_read_b128 v[172:175], v231 offset:3072
	ds_read_b128 v[190:193], v231 offset:4096
	ds_read_b128 v[194:197], v231 offset:5120
	ds_read_b128 v[198:201], v231 offset:6144
	ds_read_b128 v[232:235], v231 offset:7168
	global_load_lds_dwordx4 v[202:203], off
	v_lshl_add_u64 v[202:203], s[8:9], 0, v[186:187]
	s_add_i32 m0, s21, 0xe000
	s_nop 0
	global_load_lds_dwordx4 v[202:203], off
	s_waitcnt vmcnt(8)
	s_waitcnt lgkmcnt(0)
	s_barrier
	s_setprio 1
	s_waitcnt lgkmcnt(0)
	v_mfma_f32_16x16x32_bf16 v[124:127], v[128:131], v[160:163], v[124:127]
	v_mfma_f32_16x16x32_bf16 v[120:123], v[136:139], v[160:163], v[120:123]
	v_mfma_f32_16x16x32_bf16 v[108:111], v[128:131], v[168:171], v[108:111]
	v_mfma_f32_16x16x32_bf16 v[104:107], v[136:139], v[168:171], v[104:107]
	v_mfma_f32_16x16x32_bf16 v[92:95], v[128:131], v[190:193], v[92:95]
	v_mfma_f32_16x16x32_bf16 v[88:91], v[136:139], v[190:193], v[88:91]
	v_mfma_f32_16x16x32_bf16 v[76:79], v[128:131], v[198:201], v[76:79]
	v_mfma_f32_16x16x32_bf16 v[72:75], v[136:139], v[198:201], v[72:75]
	v_mfma_f32_16x16x32_bf16 v[124:127], v[132:135], v[164:167], v[124:127]
	v_mfma_f32_16x16x32_bf16 v[120:123], v[140:143], v[164:167], v[120:123]
	v_mfma_f32_16x16x32_bf16 v[108:111], v[132:135], v[172:175], v[108:111]
	v_mfma_f32_16x16x32_bf16 v[104:107], v[140:143], v[172:175], v[104:107]
	v_mfma_f32_16x16x32_bf16 v[92:95], v[132:135], v[194:197], v[92:95]
	v_mfma_f32_16x16x32_bf16 v[88:91], v[140:143], v[194:197], v[88:91]
	v_mfma_f32_16x16x32_bf16 v[76:79], v[132:135], v[232:235], v[76:79]
	v_mfma_f32_16x16x32_bf16 v[72:75], v[140:143], v[232:235], v[72:75]
	s_setprio 0
	s_setprio 1
	v_mfma_f32_16x16x32_bf16 v[116:119], v[144:147], v[160:163], v[116:119]
	v_mfma_f32_16x16x32_bf16 v[112:115], v[152:155], v[160:163], v[112:115]
	v_mfma_f32_16x16x32_bf16 v[100:103], v[144:147], v[168:171], v[100:103]
	v_mfma_f32_16x16x32_bf16 v[96:99], v[152:155], v[168:171], v[96:99]
	v_mfma_f32_16x16x32_bf16 v[84:87], v[144:147], v[190:193], v[84:87]
	v_mfma_f32_16x16x32_bf16 v[80:83], v[152:155], v[190:193], v[80:83]
	v_mfma_f32_16x16x32_bf16 v[68:71], v[144:147], v[198:201], v[68:71]
	v_mfma_f32_16x16x32_bf16 v[64:67], v[152:155], v[198:201], v[64:67]
	v_mfma_f32_16x16x32_bf16 v[116:119], v[148:151], v[164:167], v[116:119]
	v_mfma_f32_16x16x32_bf16 v[112:115], v[156:159], v[164:167], v[112:115]
	v_mfma_f32_16x16x32_bf16 v[100:103], v[148:151], v[172:175], v[100:103]
	v_mfma_f32_16x16x32_bf16 v[96:99], v[156:159], v[172:175], v[96:99]
	v_mfma_f32_16x16x32_bf16 v[84:87], v[148:151], v[194:197], v[84:87]
	v_mfma_f32_16x16x32_bf16 v[80:83], v[156:159], v[194:197], v[80:83]
	v_mfma_f32_16x16x32_bf16 v[68:71], v[148:151], v[232:235], v[68:71]
	v_mfma_f32_16x16x32_bf16 v[64:67], v[156:159], v[232:235], v[64:67]
	s_setprio 0
	s_barrier
	s_add_i32 vcc_lo, vcc_lo, s20
	v_lshl_add_u64 v[202:203], s[44:45], 0, v[176:177]
	s_mov_b32 m0, vcc_lo
	ds_read_b128 v[160:163], v231 offset:16384
	ds_read_b128 v[164:167], v231 offset:17408
	ds_read_b128 v[168:171], v231 offset:18432
	ds_read_b128 v[172:175], v231 offset:19456
	ds_read_b128 v[190:193], v231 offset:20480
	ds_read_b128 v[194:197], v231 offset:21504
	ds_read_b128 v[198:201], v231 offset:22528
	ds_read_b128 v[232:235], v231 offset:23552
	global_load_lds_dwordx4 v[202:203], off
	s_add_i32 m0, vcc_lo, 0x2000
	v_lshl_add_u64 v[236:237], s[44:45], 0, v[184:185]
	s_add_u32 s44, s44, s6
	s_addc_u32 s45, s45, 0
	s_add_i32 s15, s15, s20
	global_load_lds_dwordx4 v[236:237], off
	v_lshl_add_u64 v[238:239], s[44:45], 0, v[176:177]
	s_mov_b32 m0, s15
	v_lshl_add_u64 v[240:241], s[44:45], 0, v[184:185]
	global_load_lds_dwordx4 v[238:239], off
	s_add_i32 m0, s15, 0x2000
	v_lshl_add_u64 v[242:243], s[10:11], 0, v[180:181]
	global_load_lds_dwordx4 v[240:241], off
	s_mov_b32 m0, s21
	v_lshl_add_u64 v[244:245], s[10:11], 0, v[182:183]
	global_load_lds_dwordx4 v[242:243], off
	s_mov_b32 m0, s88
	s_nop 0
	global_load_lds_dwordx4 v[244:245], off
	s_waitcnt vmcnt(8)
	s_waitcnt lgkmcnt(0)
	s_barrier
	s_setprio 1
	s_waitcnt lgkmcnt(0)
	v_mfma_f32_16x16x32_bf16 v[60:63], v[128:131], v[160:163], v[60:63]
	v_mfma_f32_16x16x32_bf16 v[56:59], v[136:139], v[160:163], v[56:59]
	v_mfma_f32_16x16x32_bf16 v[44:47], v[128:131], v[168:171], v[44:47]
	v_mfma_f32_16x16x32_bf16 v[40:43], v[136:139], v[168:171], v[40:43]
	v_mfma_f32_16x16x32_bf16 v[28:31], v[128:131], v[190:193], v[28:31]
	v_mfma_f32_16x16x32_bf16 v[24:27], v[136:139], v[190:193], v[24:27]
	v_mfma_f32_16x16x32_bf16 v[12:15], v[128:131], v[198:201], v[12:15]
	v_mfma_f32_16x16x32_bf16 v[8:11], v[136:139], v[198:201], v[8:11]
	v_mfma_f32_16x16x32_bf16 v[60:63], v[132:135], v[164:167], v[60:63]
	v_mfma_f32_16x16x32_bf16 v[56:59], v[140:143], v[164:167], v[56:59]
	v_mfma_f32_16x16x32_bf16 v[44:47], v[132:135], v[172:175], v[44:47]
	v_mfma_f32_16x16x32_bf16 v[40:43], v[140:143], v[172:175], v[40:43]
	v_mfma_f32_16x16x32_bf16 v[28:31], v[132:135], v[194:197], v[28:31]
	v_mfma_f32_16x16x32_bf16 v[24:27], v[140:143], v[194:197], v[24:27]
	v_mfma_f32_16x16x32_bf16 v[12:15], v[132:135], v[232:235], v[12:15]
	v_mfma_f32_16x16x32_bf16 v[8:11], v[140:143], v[232:235], v[8:11]
	s_setprio 0
	s_setprio 1
	v_mfma_f32_16x16x32_bf16 v[52:55], v[144:147], v[160:163], v[52:55]
	v_mfma_f32_16x16x32_bf16 v[48:51], v[152:155], v[160:163], v[48:51]
	v_mfma_f32_16x16x32_bf16 v[36:39], v[144:147], v[168:171], v[36:39]
	v_mfma_f32_16x16x32_bf16 v[32:35], v[152:155], v[168:171], v[32:35]
	v_mfma_f32_16x16x32_bf16 v[20:23], v[144:147], v[190:193], v[20:23]
	v_mfma_f32_16x16x32_bf16 v[16:19], v[152:155], v[190:193], v[16:19]
	v_mfma_f32_16x16x32_bf16 v[4:7], v[144:147], v[198:201], v[4:7]
	v_mfma_f32_16x16x32_bf16 v[0:3], v[152:155], v[198:201], v[0:3]
	v_mfma_f32_16x16x32_bf16 v[52:55], v[148:151], v[164:167], v[52:55]
	v_mfma_f32_16x16x32_bf16 v[48:51], v[156:159], v[164:167], v[48:51]
	v_mfma_f32_16x16x32_bf16 v[36:39], v[148:151], v[172:175], v[36:39]
	v_mfma_f32_16x16x32_bf16 v[32:35], v[156:159], v[172:175], v[32:35]
	v_mfma_f32_16x16x32_bf16 v[20:23], v[148:151], v[194:197], v[20:23]
	v_mfma_f32_16x16x32_bf16 v[16:19], v[156:159], v[194:197], v[16:19]
	v_mfma_f32_16x16x32_bf16 v[4:7], v[148:151], v[232:235], v[4:7]
	v_mfma_f32_16x16x32_bf16 v[0:3], v[156:159], v[232:235], v[0:3]
	s_setprio 0
	s_barrier
	s_add_i32 s15, 0, 0x18000
	s_add_i32 s44, 0, 0x1c000
	v_add_u32_e32 v140, s15, v229
	v_add_u32_e32 v156, s44, v229
	ds_read_b128 v[128:131], v140
	ds_read_b128 v[132:135], v140 offset:1024
	ds_read_b128 v[136:139], v140 offset:2048
	ds_read_b128 v[140:143], v140 offset:3072
	ds_read_b128 v[144:147], v156
	ds_read_b128 v[148:151], v156 offset:1024
	ds_read_b128 v[152:155], v156 offset:2048
	ds_read_b128 v[156:159], v156 offset:3072
	s_add_u32 s10, s10, s6
	s_addc_u32 s11, s11, 0
	s_mov_b32 m0, s89
	v_lshl_add_u64 v[246:247], s[10:11], 0, v[180:181]
	ds_read_b128 v[160:163], v231 offset:32768
	ds_read_b128 v[164:167], v231 offset:33792
	ds_read_b128 v[168:171], v231 offset:34816
	ds_read_b128 v[172:175], v231 offset:35840
	ds_read_b128 v[190:193], v231 offset:36864
	ds_read_b128 v[194:197], v231 offset:37888
	ds_read_b128 v[198:201], v231 offset:38912
	ds_read_b128 v[232:235], v231 offset:39936
	global_load_lds_dwordx4 v[246:247], off
	v_lshl_add_u64 v[246:247], s[10:11], 0, v[182:183]
	s_mov_b32 m0, s93
	s_nop 0
	global_load_lds_dwordx4 v[246:247], off
	s_waitcnt vmcnt(8)
	s_waitcnt lgkmcnt(0)
	s_barrier
	s_setprio 1
	s_waitcnt lgkmcnt(0)
	v_mfma_f32_16x16x32_bf16 v[124:127], v[128:131], v[160:163], v[124:127]
	v_mfma_f32_16x16x32_bf16 v[120:123], v[136:139], v[160:163], v[120:123]
	v_mfma_f32_16x16x32_bf16 v[108:111], v[128:131], v[168:171], v[108:111]
	v_mfma_f32_16x16x32_bf16 v[104:107], v[136:139], v[168:171], v[104:107]
	v_mfma_f32_16x16x32_bf16 v[92:95], v[128:131], v[190:193], v[92:95]
	v_mfma_f32_16x16x32_bf16 v[88:91], v[136:139], v[190:193], v[88:91]
	v_mfma_f32_16x16x32_bf16 v[76:79], v[128:131], v[198:201], v[76:79]
	v_mfma_f32_16x16x32_bf16 v[72:75], v[136:139], v[198:201], v[72:75]
	v_mfma_f32_16x16x32_bf16 v[124:127], v[132:135], v[164:167], v[124:127]
	v_mfma_f32_16x16x32_bf16 v[120:123], v[140:143], v[164:167], v[120:123]
	v_mfma_f32_16x16x32_bf16 v[108:111], v[132:135], v[172:175], v[108:111]
	v_mfma_f32_16x16x32_bf16 v[104:107], v[140:143], v[172:175], v[104:107]
	v_mfma_f32_16x16x32_bf16 v[92:95], v[132:135], v[194:197], v[92:95]
	v_mfma_f32_16x16x32_bf16 v[88:91], v[140:143], v[194:197], v[88:91]
	v_mfma_f32_16x16x32_bf16 v[76:79], v[132:135], v[232:235], v[76:79]
	v_mfma_f32_16x16x32_bf16 v[72:75], v[140:143], v[232:235], v[72:75]
	s_setprio 0
	s_setprio 1
	v_mfma_f32_16x16x32_bf16 v[116:119], v[144:147], v[160:163], v[116:119]
	v_mfma_f32_16x16x32_bf16 v[112:115], v[152:155], v[160:163], v[112:115]
	v_mfma_f32_16x16x32_bf16 v[100:103], v[144:147], v[168:171], v[100:103]
	v_mfma_f32_16x16x32_bf16 v[96:99], v[152:155], v[168:171], v[96:99]
	v_mfma_f32_16x16x32_bf16 v[84:87], v[144:147], v[190:193], v[84:87]
	v_mfma_f32_16x16x32_bf16 v[80:83], v[152:155], v[190:193], v[80:83]
	v_mfma_f32_16x16x32_bf16 v[68:71], v[144:147], v[198:201], v[68:71]
	v_mfma_f32_16x16x32_bf16 v[64:67], v[152:155], v[198:201], v[64:67]
	v_mfma_f32_16x16x32_bf16 v[116:119], v[148:151], v[164:167], v[116:119]
	v_mfma_f32_16x16x32_bf16 v[112:115], v[156:159], v[164:167], v[112:115]
	v_mfma_f32_16x16x32_bf16 v[100:103], v[148:151], v[172:175], v[100:103]
	v_mfma_f32_16x16x32_bf16 v[96:99], v[156:159], v[172:175], v[96:99]
	v_mfma_f32_16x16x32_bf16 v[84:87], v[148:151], v[194:197], v[84:87]
	v_mfma_f32_16x16x32_bf16 v[80:83], v[156:159], v[194:197], v[80:83]
	v_mfma_f32_16x16x32_bf16 v[68:71], v[148:151], v[232:235], v[68:71]
	v_mfma_f32_16x16x32_bf16 v[64:67], v[156:159], v[232:235], v[64:67]
	s_setprio 0
	s_barrier
	s_add_i32 s10, s15, s20
	v_lshl_add_u64 v[202:203], v[202:203], 0, s[30:31]
	s_mov_b32 m0, s10
	ds_read_b128 v[160:163], v231 offset:49152
	ds_read_b128 v[164:167], v231 offset:50176
	ds_read_b128 v[168:171], v231 offset:51200
	ds_read_b128 v[172:175], v231 offset:52224
	ds_read_b128 v[190:193], v231 offset:53248
	ds_read_b128 v[194:197], v231 offset:54272
	ds_read_b128 v[198:201], v231 offset:55296
	ds_read_b128 v[232:235], v231 offset:56320
	global_load_lds_dwordx4 v[202:203], off
	v_lshl_add_u64 v[202:203], v[236:237], 0, s[30:31]
	s_add_i32 m0, s10, 0x2000
	s_add_i32 s10, s44, s20
	global_load_lds_dwordx4 v[202:203], off
	v_lshl_add_u64 v[202:203], v[238:239], 0, s[30:31]
	s_mov_b32 m0, s10
	s_nop 0
	global_load_lds_dwordx4 v[202:203], off
	v_lshl_add_u64 v[202:203], v[240:241], 0, s[30:31]
	s_add_i32 m0, s10, 0x2000
	s_nop 0
	global_load_lds_dwordx4 v[202:203], off
	v_lshl_add_u64 v[202:203], v[242:243], 0, s[30:31]
	s_mov_b32 m0, s96
	s_nop 0
	global_load_lds_dwordx4 v[202:203], off
	v_lshl_add_u64 v[202:203], v[244:245], 0, s[30:31]
	s_mov_b32 m0, s97
	s_nop 0
	global_load_lds_dwordx4 v[202:203], off
	s_waitcnt vmcnt(8)
	s_waitcnt lgkmcnt(0)
	s_barrier
	s_setprio 1
	s_waitcnt lgkmcnt(0)
	v_mfma_f32_16x16x32_bf16 v[60:63], v[128:131], v[160:163], v[60:63]
	v_mfma_f32_16x16x32_bf16 v[56:59], v[136:139], v[160:163], v[56:59]
	v_mfma_f32_16x16x32_bf16 v[44:47], v[128:131], v[168:171], v[44:47]
	v_mfma_f32_16x16x32_bf16 v[40:43], v[136:139], v[168:171], v[40:43]
	v_mfma_f32_16x16x32_bf16 v[28:31], v[128:131], v[190:193], v[28:31]
	v_mfma_f32_16x16x32_bf16 v[24:27], v[136:139], v[190:193], v[24:27]
	v_mfma_f32_16x16x32_bf16 v[12:15], v[128:131], v[198:201], v[12:15]
	v_mfma_f32_16x16x32_bf16 v[8:11], v[136:139], v[198:201], v[8:11]
	v_mfma_f32_16x16x32_bf16 v[60:63], v[132:135], v[164:167], v[60:63]
	v_mfma_f32_16x16x32_bf16 v[56:59], v[140:143], v[164:167], v[56:59]
	v_mfma_f32_16x16x32_bf16 v[44:47], v[132:135], v[172:175], v[44:47]
	v_mfma_f32_16x16x32_bf16 v[40:43], v[140:143], v[172:175], v[40:43]
	v_mfma_f32_16x16x32_bf16 v[28:31], v[132:135], v[194:197], v[28:31]
	v_mfma_f32_16x16x32_bf16 v[24:27], v[140:143], v[194:197], v[24:27]
	v_mfma_f32_16x16x32_bf16 v[12:15], v[132:135], v[232:235], v[12:15]
	v_mfma_f32_16x16x32_bf16 v[8:11], v[140:143], v[232:235], v[8:11]
	s_setprio 0
	s_setprio 1
	v_mfma_f32_16x16x32_bf16 v[52:55], v[144:147], v[160:163], v[52:55]
	v_mfma_f32_16x16x32_bf16 v[48:51], v[152:155], v[160:163], v[48:51]
	v_mfma_f32_16x16x32_bf16 v[36:39], v[144:147], v[168:171], v[36:39]
	v_mfma_f32_16x16x32_bf16 v[32:35], v[152:155], v[168:171], v[32:35]
	v_mfma_f32_16x16x32_bf16 v[20:23], v[144:147], v[190:193], v[20:23]
	v_mfma_f32_16x16x32_bf16 v[16:19], v[152:155], v[190:193], v[16:19]
	v_mfma_f32_16x16x32_bf16 v[4:7], v[144:147], v[198:201], v[4:7]
	v_mfma_f32_16x16x32_bf16 v[0:3], v[152:155], v[198:201], v[0:3]
	v_mfma_f32_16x16x32_bf16 v[52:55], v[148:151], v[164:167], v[52:55]
	v_mfma_f32_16x16x32_bf16 v[48:51], v[156:159], v[164:167], v[48:51]
	v_mfma_f32_16x16x32_bf16 v[36:39], v[148:151], v[172:175], v[36:39]
	v_mfma_f32_16x16x32_bf16 v[32:35], v[156:159], v[172:175], v[32:35]
	v_mfma_f32_16x16x32_bf16 v[20:23], v[148:151], v[194:197], v[20:23]
	v_mfma_f32_16x16x32_bf16 v[16:19], v[156:159], v[194:197], v[16:19]
	v_mfma_f32_16x16x32_bf16 v[4:7], v[148:151], v[232:235], v[4:7]
	v_mfma_f32_16x16x32_bf16 v[0:3], v[156:159], v[232:235], v[0:3]
	s_setprio 0
	s_barrier
	s_add_u32 s12, s12, 0x100
	s_addc_u32 s13, s13, 0
	s_add_u32 s8, s8, 0x100
	s_addc_u32 s9, s9, 0
	s_cmp_ge_u32 s14, s80
	s_mov_b32 s10, s14
	s_cbranch_scc0 .LBB0_93
	s_and_b64 vcc, exec, s[64:65]
	s_cbranch_vccz .LBB0_130
	s_barrier
	v_lshl_add_u32 v190, s85, 8, v228
	s_mov_b64 s[8:9], -1
	s_and_b64 vcc, exec, s[54:55]
	s_cbranch_vccnz .LBB0_131

.LBB0_198:
	global_load_dwordx2 v[92:93], v[84:85], off
	global_load_dwordx2 v[98:99], v[84:85], off offset:512
	global_load_dwordx2 v[100:101], v[84:85], off offset:1024
	global_load_dwordx2 v[102:103], v[84:85], off offset:1536
	global_load_dwordx2 v[104:105], v[84:85], off offset:2048
	global_load_dwordx2 v[106:107], v[84:85], off offset:2560
	global_load_dwordx2 v[108:109], v[84:85], off offset:3072
	global_load_dwordx2 v[110:111], v[84:85], off offset:3584
	s_nop 0
	v_pk_mul_f32 v[94:95], v[78:79], v[76:77] op_sel:[0,1] op_sel_hi:[1,0]
	s_add_i32 s13, s13, 8
	v_pk_fma_f32 v[96:97], v[80:81], v[76:77], v[94:95] neg_lo:[0,0,1] neg_hi:[0,0,1]
	v_pk_fma_f32 v[76:77], v[80:81], v[76:77], v[94:95]
	s_cmp_eq_u32 s6, s13
	v_mov_b32_e32 v97, v77
	s_waitcnt vmcnt(7)
	v_pk_add_f32 v[76:77], v[96:97], v[92:93]
	s_nop 0
	v_pk_mul_f32 v[94:95], v[78:79], v[76:77] op_sel:[0,1] op_sel_hi:[1,0]
	s_nop 0
	v_pk_fma_f32 v[96:97], v[80:81], v[76:77], v[94:95] neg_lo:[0,0,1] neg_hi:[0,0,1]
	v_pk_fma_f32 v[76:77], v[80:81], v[76:77], v[94:95]
	s_nop 0
	v_mov_b32_e32 v97, v77
	s_waitcnt vmcnt(6)
	v_pk_add_f32 v[76:77], v[96:97], v[98:99]
	s_nop 0
	v_pk_mul_f32 v[94:95], v[78:79], v[76:77] op_sel:[0,1] op_sel_hi:[1,0]
	s_nop 0
	v_pk_fma_f32 v[96:97], v[80:81], v[76:77], v[94:95] neg_lo:[0,0,1] neg_hi:[0,0,1]
	v_pk_fma_f32 v[76:77], v[80:81], v[76:77], v[94:95]
	s_nop 0
	v_mov_b32_e32 v97, v77
	s_waitcnt vmcnt(5)
	v_pk_add_f32 v[76:77], v[96:97], v[100:101]
	s_nop 0
	v_pk_mul_f32 v[94:95], v[78:79], v[76:77] op_sel:[0,1] op_sel_hi:[1,0]
	s_nop 0
	v_pk_fma_f32 v[96:97], v[80:81], v[76:77], v[94:95] neg_lo:[0,0,1] neg_hi:[0,0,1]
	v_pk_fma_f32 v[76:77], v[80:81], v[76:77], v[94:95]
	s_nop 0
	v_mov_b32_e32 v97, v77
	s_waitcnt vmcnt(4)
	v_pk_add_f32 v[76:77], v[96:97], v[102:103]
	s_nop 0
	v_pk_mul_f32 v[94:95], v[78:79], v[76:77] op_sel:[0,1] op_sel_hi:[1,0]
	s_nop 0
	v_pk_fma_f32 v[96:97], v[80:81], v[76:77], v[94:95] neg_lo:[0,0,1] neg_hi:[0,0,1]
	v_pk_fma_f32 v[76:77], v[80:81], v[76:77], v[94:95]
	s_nop 0
	v_mov_b32_e32 v97, v77
	s_waitcnt vmcnt(3)
	v_pk_add_f32 v[76:77], v[96:97], v[104:105]
	s_nop 0
	v_pk_mul_f32 v[94:95], v[78:79], v[76:77] op_sel:[0,1] op_sel_hi:[1,0]
	s_nop 0
	v_pk_fma_f32 v[96:97], v[80:81], v[76:77], v[94:95] neg_lo:[0,0,1] neg_hi:[0,0,1]
	v_pk_fma_f32 v[76:77], v[80:81], v[76:77], v[94:95]
	s_nop 0
	v_mov_b32_e32 v97, v77
	s_waitcnt vmcnt(2)
	v_pk_add_f32 v[76:77], v[96:97], v[106:107]
	s_nop 0
	v_pk_mul_f32 v[94:95], v[78:79], v[76:77] op_sel:[0,1] op_sel_hi:[1,0]
	s_nop 0
	v_pk_fma_f32 v[96:97], v[80:81], v[76:77], v[94:95] neg_lo:[0,0,1] neg_hi:[0,0,1]
	v_pk_fma_f32 v[76:77], v[80:81], v[76:77], v[94:95]
	s_nop 0
	v_mov_b32_e32 v97, v77
	s_waitcnt vmcnt(1)
	v_pk_add_f32 v[76:77], v[96:97], v[108:109]
	s_nop 0
	v_pk_mul_f32 v[94:95], v[78:79], v[76:77] op_sel:[0,1] op_sel_hi:[1,0]
	v_lshl_add_u64 v[84:85], v[84:85], 0, s[24:25]
	v_pk_fma_f32 v[96:97], v[80:81], v[76:77], v[94:95] neg_lo:[0,0,1] neg_hi:[0,0,1]
	v_pk_fma_f32 v[76:77], v[80:81], v[76:77], v[94:95]
	s_nop 0
	v_mov_b32_e32 v97, v77
	s_waitcnt vmcnt(0) lgkmcnt(0)
	v_pk_add_f32 v[76:77], v[96:97], v[110:111]
	s_cbranch_scc0 .LBB0_198
	s_andn2_b64 vcc, exec, s[44:45]
	s_cbranch_vccz .LBB0_204
	s_branch .LBB0_206

.LBB0_205:
	s_mov_b64 s[14:15], 0x200
	global_load_dwordx2 v[92:93], v[84:85], off
	global_load_dwordx2 v[98:99], v[84:85], off offset:512
	global_load_dwordx2 v[100:101], v[84:85], off offset:1024
	global_load_dwordx2 v[102:103], v[84:85], off offset:1536
	global_load_dwordx2 v[104:105], v[84:85], off offset:2048
	global_load_dwordx2 v[106:107], v[84:85], off offset:2560
	global_load_dwordx2 v[108:109], v[84:85], off offset:3072
	s_nop 0
	v_pk_mul_f32 v[94:95], v[78:79], v[76:77] op_sel:[0,1] op_sel_hi:[1,0]
	s_nop 0
	v_pk_fma_f32 v[96:97], v[80:81], v[76:77], v[94:95] neg_lo:[0,0,1] neg_hi:[0,0,1]
	v_pk_fma_f32 v[76:77], v[80:81], v[76:77], v[94:95]
	s_nop 0
	v_mov_b32_e32 v97, v77
	s_waitcnt vmcnt(6)
	v_pk_add_f32 v[76:77], v[96:97], v[92:93]
	s_cmp_eq_u32 s6, 1
	s_cbranch_scc1 .Lrem_done
	s_nop 0
	v_pk_mul_f32 v[94:95], v[78:79], v[76:77] op_sel:[0,1] op_sel_hi:[1,0]
	s_nop 0
	v_pk_fma_f32 v[96:97], v[80:81], v[76:77], v[94:95] neg_lo:[0,0,1] neg_hi:[0,0,1]
	v_pk_fma_f32 v[76:77], v[80:81], v[76:77], v[94:95]
	s_nop 0
	v_mov_b32_e32 v97, v77
	s_waitcnt vmcnt(5)
	v_pk_add_f32 v[76:77], v[96:97], v[98:99]
	s_cmp_eq_u32 s6, 2
	s_cbranch_scc1 .Lrem_done
	s_nop 0
	v_pk_mul_f32 v[94:95], v[78:79], v[76:77] op_sel:[0,1] op_sel_hi:[1,0]
	s_nop 0
	v_pk_fma_f32 v[96:97], v[80:81], v[76:77], v[94:95] neg_lo:[0,0,1] neg_hi:[0,0,1]
	v_pk_fma_f32 v[76:77], v[80:81], v[76:77], v[94:95]
	s_nop 0
	v_mov_b32_e32 v97, v77
	s_waitcnt vmcnt(4)
	v_pk_add_f32 v[76:77], v[96:97], v[100:101]
	s_cmp_eq_u32 s6, 3
	s_cbranch_scc1 .Lrem_done
	s_nop 0
	v_pk_mul_f32 v[94:95], v[78:79], v[76:77] op_sel:[0,1] op_sel_hi:[1,0]
	s_nop 0
	v_pk_fma_f32 v[96:97], v[80:81], v[76:77], v[94:95] neg_lo:[0,0,1] neg_hi:[0,0,1]
	v_pk_fma_f32 v[76:77], v[80:81], v[76:77], v[94:95]
	s_nop 0
	v_mov_b32_e32 v97, v77
	s_waitcnt vmcnt(3)
	v_pk_add_f32 v[76:77], v[96:97], v[102:103]
	s_cmp_eq_u32 s6, 4
	s_cbranch_scc1 .Lrem_done
	s_nop 0
	v_pk_mul_f32 v[94:95], v[78:79], v[76:77] op_sel:[0,1] op_sel_hi:[1,0]
	s_nop 0
	v_pk_fma_f32 v[96:97], v[80:81], v[76:77], v[94:95] neg_lo:[0,0,1] neg_hi:[0,0,1]
	v_pk_fma_f32 v[76:77], v[80:81], v[76:77], v[94:95]
	s_nop 0
	v_mov_b32_e32 v97, v77
	s_waitcnt vmcnt(2)
	v_pk_add_f32 v[76:77], v[96:97], v[104:105]
	s_cmp_eq_u32 s6, 5
	s_cbranch_scc1 .Lrem_done
	s_nop 0
	v_pk_mul_f32 v[94:95], v[78:79], v[76:77] op_sel:[0,1] op_sel_hi:[1,0]
	s_nop 0
	v_pk_fma_f32 v[96:97], v[80:81], v[76:77], v[94:95] neg_lo:[0,0,1] neg_hi:[0,0,1]
	v_pk_fma_f32 v[76:77], v[80:81], v[76:77], v[94:95]
	s_nop 0
	v_mov_b32_e32 v97, v77
	s_waitcnt vmcnt(1)
	v_pk_add_f32 v[76:77], v[96:97], v[106:107]
	s_cmp_eq_u32 s6, 6
	s_cbranch_scc1 .Lrem_done
	s_nop 0
	v_pk_mul_f32 v[94:95], v[78:79], v[76:77] op_sel:[0,1] op_sel_hi:[1,0]
	s_nop 0
	v_pk_fma_f32 v[96:97], v[80:81], v[76:77], v[94:95] neg_lo:[0,0,1] neg_hi:[0,0,1]
	v_pk_fma_f32 v[76:77], v[80:81], v[76:77], v[94:95]
	s_nop 0
	v_mov_b32_e32 v97, v77
	s_waitcnt vmcnt(0)
	v_pk_add_f32 v[76:77], v[96:97], v[108:109]
.Lrem_done:
	s_waitcnt vmcnt(0) lgkmcnt(0)
